# attention round end no longer waits for the context-K image DMA (the next round K loop first counted wait covers it); on top of v43
# baseline (speedup 1.0000x reference)
; #define LAS __attribute__((address_space(3)))
; template <bool LOCAL>
; __device__ __forceinline__ void attn_unit(const bf16_t* Q, const bf16_t* KT, const bf16_t* VT, bf16_t* O, LAS unsigned char* lds, int b, int h, int r, int w, int tq, int lane) {
;     ...
;     {
;         const LAS unsigned char* vl = lds + 65536 + g * 2048 + q * 16;
; #pragma unroll
;         for (int p = 0; p < 8; ++p)
; #pragma unroll
;             for (int df = 0; df < 8; ++df) o[df] = __builtin_amdgcn_mfma_f32_16x16x32_bf16(*(const LAS bf16x8*)(vl + p * 8192 + df * 256), pb[CP + p], o[df], 0, 0, 0);
;     }
; __global__ void __launch_bounds__(NTHREADS, 2) mega(Args args) {
;     ...
;                     { const int oc0 = (ML + b * CTX) >> 3;
;                       for (int ci = tid; ci < 4096; ci += NTHREADS) { const int o = ci >> 7, wq = ci & 127;
;                           const u32x4 kv = *(const u32x4*)(KTp + ((size_t)((oc0 + o) * NH + h)) * 1024 + wq * 8);
;                           *(LAS u32x4*)(lds + o * 2048 + (wq & ~15) * 16 + ((wq & 15) ^ (o & 2)) * 16) = kv;
;                           const u32x4 vv = *(const u32x4*)(VTp + ((size_t)((oc0 + o) * NH + h)) * 1024 + wq * 8);
;                           *(LAS u32x4*)(lds + 65536 + o * 2048 + wq * 16) = vv; }
.Lrg_v_B_end:
.Lrg_v_done:
	s_barrier
	v_mov_b32_e32 v222, v234
	v_mov_b32_e32 v223, v235
	s_lshl_b32 s55, s57, 10
	s_add_i32 m0, s55, 0
	s_nop 0
	global_load_lds_dwordx4 v[222:223], off
	v_add_co_u32_e32 v222, vcc, 0x20000, v222
	s_nop 1
	v_addc_co_u32_e32 v223, vcc, 0, v223, vcc
	s_add_i32 m0, s55, 8192
	s_nop 0
	global_load_lds_dwordx4 v[222:223], off
	v_add_co_u32_e32 v222, vcc, 0x20000, v222
	s_nop 1
	v_addc_co_u32_e32 v223, vcc, 0, v223, vcc
	s_add_i32 m0, s55, 16384
	s_nop 0
	global_load_lds_dwordx4 v[222:223], off
	v_add_co_u32_e32 v222, vcc, 0x20000, v222
	s_nop 1
	v_addc_co_u32_e32 v223, vcc, 0, v223, vcc
	s_add_i32 m0, s55, 24576
	s_nop 0
	global_load_lds_dwordx4 v[222:223], off
	v_add_co_u32_e32 v222, vcc, 0x20000, v222
	s_nop 1
	v_addc_co_u32_e32 v223, vcc, 0, v223, vcc
	s_add_i32 m0, s55, 32768
	s_nop 0
	global_load_lds_dwordx4 v[222:223], off
	v_add_co_u32_e32 v222, vcc, 0x20000, v222
	s_nop 1
	v_addc_co_u32_e32 v223, vcc, 0, v223, vcc
	s_add_i32 m0, s55, 40960
	s_nop 0
	global_load_lds_dwordx4 v[222:223], off
	v_add_co_u32_e32 v222, vcc, 0x20000, v222
	s_nop 1
	v_addc_co_u32_e32 v223, vcc, 0, v223, vcc
	s_add_i32 m0, s55, 49152
	s_nop 0
	global_load_lds_dwordx4 v[222:223], off
	v_add_co_u32_e32 v222, vcc, 0x20000, v222
	s_nop 1
	v_addc_co_u32_e32 v223, vcc, 0, v223, vcc
	s_add_i32 m0, s55, 57344
	s_nop 0
	global_load_lds_dwordx4 v[222:223], off
	s_waitcnt lgkmcnt(0)
	s_add_i32 s48, s48, 2
	s_add_i32 s52, s52, s80
	s_sub_i32 s51, s51, s80
	s_lshl_b32 s82, s80, 6
	v_add_u32_e32 v162, s82, v162
	s_cmp_eq_u32 s48, 8
	ds_read_b128 v[200:203], v178
	ds_read_b128 v[204:207], v178 offset:256
	ds_read_b128 v[208:211], v178 offset:512
	ds_read_b128 v[212:215], v178 offset:768
	ds_read_b128 v[216:219], v178 offset:1024
	ds_read_b128 v[220:223], v178 offset:1280
	ds_read_b128 v[224:227], v178 offset:1536
	ds_read_b128 v[228:231], v178 offset:1792
	s_waitcnt lgkmcnt(7)
	v_mfma_f32_16x16x32_bf16 v[22:25], v[200:203], v[98:101], v[22:25]
	ds_read_b128 v[200:203], v178 offset:8192
	s_waitcnt lgkmcnt(7)
	v_mfma_f32_16x16x32_bf16 v[30:33], v[204:207], v[98:101], v[30:33]
	ds_read_b128 v[204:207], v178 offset:8448
	s_waitcnt lgkmcnt(7)
	v_mfma_f32_16x16x32_bf16 v[34:37], v[208:211], v[98:101], v[34:37]
	ds_read_b128 v[208:211], v178 offset:8704
	s_waitcnt lgkmcnt(7)
	v_mfma_f32_16x16x32_bf16 v[38:41], v[212:215], v[98:101], v[38:41]
	ds_read_b128 v[212:215], v178 offset:8960
	s_waitcnt lgkmcnt(7)
	v_mfma_f32_16x16x32_bf16 v[42:45], v[216:219], v[98:101], v[42:45]
	ds_read_b128 v[216:219], v178 offset:9216
	s_waitcnt lgkmcnt(7)
	v_mfma_f32_16x16x32_bf16 v[46:49], v[220:223], v[98:101], v[46:49]
	ds_read_b128 v[220:223], v178 offset:9472
	s_waitcnt lgkmcnt(7)
	v_mfma_f32_16x16x32_bf16 v[50:53], v[224:227], v[98:101], v[50:53]
	ds_read_b128 v[224:227], v178 offset:9728
	s_waitcnt lgkmcnt(7)
	v_mfma_f32_16x16x32_bf16 v[54:57], v[228:231], v[98:101], v[54:57]
	ds_read_b128 v[228:231], v178 offset:9984
	s_waitcnt lgkmcnt(7)
	v_mfma_f32_16x16x32_bf16 v[22:25], v[200:203], v[90:93], v[22:25]
	ds_read_b128 v[200:203], v178 offset:16384
	s_waitcnt lgkmcnt(7)
	v_mfma_f32_16x16x32_bf16 v[30:33], v[204:207], v[90:93], v[30:33]
	ds_read_b128 v[204:207], v178 offset:16640
	s_waitcnt lgkmcnt(7)
	v_mfma_f32_16x16x32_bf16 v[34:37], v[208:211], v[90:93], v[34:37]
	ds_read_b128 v[208:211], v178 offset:16896
	s_waitcnt lgkmcnt(7)
	v_mfma_f32_16x16x32_bf16 v[38:41], v[212:215], v[90:93], v[38:41]
	ds_read_b128 v[212:215], v178 offset:17152
	s_waitcnt lgkmcnt(7)
	v_mfma_f32_16x16x32_bf16 v[42:45], v[216:219], v[90:93], v[42:45]
	ds_read_b128 v[216:219], v178 offset:17408
	s_waitcnt lgkmcnt(7)
	v_mfma_f32_16x16x32_bf16 v[46:49], v[220:223], v[90:93], v[46:49]
	ds_read_b128 v[220:223], v178 offset:17664
	s_waitcnt lgkmcnt(7)
	v_mfma_f32_16x16x32_bf16 v[50:53], v[224:227], v[90:93], v[50:53]
	ds_read_b128 v[224:227], v178 offset:17920
	s_waitcnt lgkmcnt(7)
	v_mfma_f32_16x16x32_bf16 v[54:57], v[228:231], v[90:93], v[54:57]
	ds_read_b128 v[228:231], v178 offset:18176
	s_waitcnt lgkmcnt(7)
	v_mfma_f32_16x16x32_bf16 v[22:25], v[200:203], v[26:29], v[22:25]
	ds_read_b128 v[200:203], v178 offset:24576
	s_waitcnt lgkmcnt(7)
	v_mfma_f32_16x16x32_bf16 v[30:33], v[204:207], v[26:29], v[30:33]
	ds_read_b128 v[204:207], v178 offset:24832
	s_waitcnt lgkmcnt(7)
	v_mfma_f32_16x16x32_bf16 v[34:37], v[208:211], v[26:29], v[34:37]
	ds_read_b128 v[208:211], v178 offset:25088
	s_waitcnt lgkmcnt(7)
	v_mfma_f32_16x16x32_bf16 v[38:41], v[212:215], v[26:29], v[38:41]
	ds_read_b128 v[212:215], v178 offset:25344
	s_waitcnt lgkmcnt(7)
	v_mfma_f32_16x16x32_bf16 v[42:45], v[216:219], v[26:29], v[42:45]
	ds_read_b128 v[216:219], v178 offset:25600
	s_waitcnt lgkmcnt(7)
	v_mfma_f32_16x16x32_bf16 v[46:49], v[220:223], v[26:29], v[46:49]
	ds_read_b128 v[220:223], v178 offset:25856
	s_waitcnt lgkmcnt(7)
	v_mfma_f32_16x16x32_bf16 v[50:53], v[224:227], v[26:29], v[50:53]
	ds_read_b128 v[224:227], v178 offset:26112
	s_waitcnt lgkmcnt(7)
	v_mfma_f32_16x16x32_bf16 v[26:29], v[228:231], v[26:29], v[54:57]
	ds_read_b128 v[228:231], v178 offset:26368
	s_waitcnt lgkmcnt(7)
	v_mfma_f32_16x16x32_bf16 v[22:25], v[200:203], v[10:13], v[22:25]
	ds_read_b128 v[200:203], v178 offset:32768
	s_waitcnt lgkmcnt(7)
	v_mfma_f32_16x16x32_bf16 v[30:33], v[204:207], v[10:13], v[30:33]
	ds_read_b128 v[204:207], v178 offset:33024
	s_waitcnt lgkmcnt(7)
	v_mfma_f32_16x16x32_bf16 v[34:37], v[208:211], v[10:13], v[34:37]
	ds_read_b128 v[208:211], v178 offset:33280
	s_waitcnt lgkmcnt(7)
	v_mfma_f32_16x16x32_bf16 v[38:41], v[212:215], v[10:13], v[38:41]
	ds_read_b128 v[212:215], v178 offset:33536
	s_waitcnt lgkmcnt(7)
; #define LAS __attribute__((address_space(3)))
; __device__ __forceinline__ unsigned cvt_pk_bf16(float lo, float hi) { unsigned r; asm volatile("v_cvt_pk_bf16_f32 %0, %1, %2" : "=v"(r) : "v"(lo), "v"(hi)); return r; }
; template <bool LOCAL>
; __device__ __forceinline__ void attn_unit(const bf16_t* Q, const bf16_t* KT, const bf16_t* VT, bf16_t* O, LAS unsigned char* lds, int b, int h, int r, int w, int tq, int lane) {
;     ...
;     {
;         const LAS unsigned char* vl = lds + 65536 + g * 2048 + q * 16;
; #pragma unroll
;         for (int p = 0; p < 8; ++p)
; #pragma unroll
;             for (int df = 0; df < 8; ++df) o[df] = __builtin_amdgcn_mfma_f32_16x16x32_bf16(*(const LAS bf16x8*)(vl + p * 8192 + df * 256), pb[CP + p], o[df], 0, 0, 0);
;     }
;     const float inv = 1.f / sum;
;     bf16_t* op = O + (size_t)qrow * D + h * HD + 4 * g;
; #pragma unroll
;     for (int df = 0; df < 8; ++df) { u32x2 wv; wv.x = cvt_pk_bf16(o[df][0] * inv, o[df][1] * inv); wv.y = cvt_pk_bf16(o[df][2] * inv, o[df][3] * inv); *(u32x2*)(op + 16 * df) = wv; }
	v_mfma_f32_16x16x32_bf16 v[42:45], v[216:219], v[10:13], v[42:45]
	ds_read_b128 v[216:219], v178 offset:33792
	s_waitcnt lgkmcnt(7)
	v_mfma_f32_16x16x32_bf16 v[46:49], v[220:223], v[10:13], v[46:49]
	ds_read_b128 v[220:223], v178 offset:34048
	s_waitcnt lgkmcnt(7)
	v_mfma_f32_16x16x32_bf16 v[50:53], v[224:227], v[10:13], v[50:53]
	ds_read_b128 v[224:227], v178 offset:34304
	s_waitcnt lgkmcnt(7)
	v_mfma_f32_16x16x32_bf16 v[10:13], v[228:231], v[10:13], v[26:29]
	ds_read_b128 v[228:231], v178 offset:34560
	s_waitcnt lgkmcnt(7)
	v_mfma_f32_16x16x32_bf16 v[22:25], v[200:203], v[2:5], v[22:25]
	ds_read_b128 v[200:203], v178 offset:40960
	s_waitcnt lgkmcnt(7)
	v_mfma_f32_16x16x32_bf16 v[26:29], v[204:207], v[2:5], v[30:33]
	ds_read_b128 v[204:207], v178 offset:41216
	s_waitcnt lgkmcnt(7)
	v_mfma_f32_16x16x32_bf16 v[30:33], v[208:211], v[2:5], v[34:37]
	ds_read_b128 v[208:211], v178 offset:41472
	s_waitcnt lgkmcnt(7)
	v_mfma_f32_16x16x32_bf16 v[34:37], v[212:215], v[2:5], v[38:41]
	ds_read_b128 v[212:215], v178 offset:41728
	s_waitcnt lgkmcnt(7)
	v_mfma_f32_16x16x32_bf16 v[38:41], v[216:219], v[2:5], v[42:45]
	ds_read_b128 v[216:219], v178 offset:41984
	s_waitcnt lgkmcnt(7)
	v_mfma_f32_16x16x32_bf16 v[42:45], v[220:223], v[2:5], v[46:49]
	ds_read_b128 v[220:223], v178 offset:42240
	s_waitcnt lgkmcnt(7)
	v_mfma_f32_16x16x32_bf16 v[46:49], v[224:227], v[2:5], v[50:53]
	ds_read_b128 v[224:227], v178 offset:42496
	s_waitcnt lgkmcnt(7)
	v_mfma_f32_16x16x32_bf16 v[2:5], v[228:231], v[2:5], v[10:13]
	ds_read_b128 v[228:231], v178 offset:42752
	s_waitcnt lgkmcnt(7)
	v_mfma_f32_16x16x32_bf16 v[10:13], v[200:203], v[6:9], v[22:25]
	ds_read_b128 v[200:203], v178 offset:49152
	s_waitcnt lgkmcnt(7)
	v_mfma_f32_16x16x32_bf16 v[22:25], v[204:207], v[6:9], v[26:29]
	ds_read_b128 v[204:207], v178 offset:49408
	s_waitcnt lgkmcnt(7)
	v_mfma_f32_16x16x32_bf16 v[26:29], v[208:211], v[6:9], v[30:33]
	ds_read_b128 v[208:211], v178 offset:49664
	s_waitcnt lgkmcnt(7)
	v_mfma_f32_16x16x32_bf16 v[30:33], v[212:215], v[6:9], v[34:37]
	ds_read_b128 v[212:215], v178 offset:49920
	s_waitcnt lgkmcnt(7)
	v_mfma_f32_16x16x32_bf16 v[34:37], v[216:219], v[6:9], v[38:41]
	ds_read_b128 v[216:219], v178 offset:50176
	s_waitcnt lgkmcnt(7)
	v_mfma_f32_16x16x32_bf16 v[38:41], v[220:223], v[6:9], v[42:45]
	ds_read_b128 v[220:223], v178 offset:50432
	s_waitcnt lgkmcnt(7)
	v_mfma_f32_16x16x32_bf16 v[42:45], v[224:227], v[6:9], v[46:49]
	ds_read_b128 v[224:227], v178 offset:50688
	s_waitcnt lgkmcnt(7)
	v_mfma_f32_16x16x32_bf16 v[2:5], v[228:231], v[6:9], v[2:5]
	ds_read_b128 v[228:231], v178 offset:50944
	s_waitcnt lgkmcnt(7)
	v_mfma_f32_16x16x32_bf16 v[6:9], v[200:203], v[14:17], v[10:13]
	ds_read_b128 v[200:203], v178 offset:57344
	s_waitcnt lgkmcnt(7)
	v_mfma_f32_16x16x32_bf16 v[10:13], v[204:207], v[14:17], v[22:25]
	ds_read_b128 v[204:207], v178 offset:57600
	s_waitcnt lgkmcnt(7)
	v_mfma_f32_16x16x32_bf16 v[22:25], v[208:211], v[14:17], v[26:29]
	ds_read_b128 v[208:211], v178 offset:57856
	s_waitcnt lgkmcnt(7)
	v_mfma_f32_16x16x32_bf16 v[26:29], v[212:215], v[14:17], v[30:33]
	ds_read_b128 v[212:215], v178 offset:58112
	s_waitcnt lgkmcnt(7)
	v_mfma_f32_16x16x32_bf16 v[30:33], v[216:219], v[14:17], v[34:37]
	ds_read_b128 v[216:219], v178 offset:58368
	s_waitcnt lgkmcnt(7)
	v_mfma_f32_16x16x32_bf16 v[34:37], v[220:223], v[14:17], v[38:41]
	ds_read_b128 v[220:223], v178 offset:58624
	s_waitcnt lgkmcnt(7)
	v_mfma_f32_16x16x32_bf16 v[38:41], v[224:227], v[14:17], v[42:45]
	ds_read_b128 v[224:227], v178 offset:58880
	s_waitcnt lgkmcnt(7)
	v_mfma_f32_16x16x32_bf16 v[2:5], v[228:231], v[14:17], v[2:5]
	ds_read_b128 v[228:231], v178 offset:59136
	s_waitcnt lgkmcnt(7)
	v_mfma_f32_16x16x32_bf16 v[6:9], v[200:203], v[18:21], v[6:9]
	s_waitcnt lgkmcnt(6)
	v_mfma_f32_16x16x32_bf16 v[10:13], v[204:207], v[18:21], v[10:13]
	s_waitcnt lgkmcnt(5)
	v_mfma_f32_16x16x32_bf16 v[14:17], v[208:211], v[18:21], v[22:25]
	s_waitcnt lgkmcnt(4)
	v_mfma_f32_16x16x32_bf16 v[22:25], v[212:215], v[18:21], v[26:29]
	s_waitcnt lgkmcnt(3)
	v_mfma_f32_16x16x32_bf16 v[26:29], v[216:219], v[18:21], v[30:33]
	s_waitcnt lgkmcnt(2)
	v_mfma_f32_16x16x32_bf16 v[30:33], v[220:223], v[18:21], v[34:37]
	s_waitcnt lgkmcnt(1)
	v_mfma_f32_16x16x32_bf16 v[34:37], v[224:227], v[18:21], v[38:41]
	s_waitcnt lgkmcnt(0)
	v_mfma_f32_16x16x32_bf16 v[2:5], v[228:231], v[18:21], v[2:5]
	s_nop 7
	v_add_f32_e32 v18, v134, v135
	v_div_scale_f32 v19, s[4:5], v18, v18, 1.0
	v_rcp_f32_e32 v20, v19
	s_nop 0
	v_fma_f32 v21, -v19, v20, 1.0
	v_fmac_f32_e32 v20, v21, v20
	v_div_scale_f32 v21, vcc, 1.0, v18, 1.0
	v_mul_f32_e32 v38, v21, v20
	v_fma_f32 v39, -v19, v38, v21
	v_fmac_f32_e32 v38, v39, v20
	v_fma_f32 v19, -v19, v38, v21
	v_div_fmas_f32 v19, v19, v20, v38
	v_div_fixup_f32 v20, v19, v18, 1.0
	v_mul_f32_e32 v6, v20, v6
	v_mul_f32_e32 v7, v20, v7
	v_cvt_pk_bf16_f32 v6, v6, v7
	v_mul_f32_e32 v7, v20, v8
	v_lshl_add_u64 v[18:19], v[130:131], 1, v[160:161]
	v_mul_f32_e32 v8, v20, v9
	v_cvt_pk_bf16_f32 v7, v7, v8
	global_store_dwordx2 v[18:19], v[6:7], off
	v_mul_f32_e32 v6, v20, v10
	v_mul_f32_e32 v7, v20, v11
	v_cvt_pk_bf16_f32 v6, v6, v7
	v_mul_f32_e32 v7, v20, v12
	v_mul_f32_e32 v8, v20, v13
	v_cvt_pk_bf16_f32 v7, v7, v8
	global_store_dwordx2 v[18:19], v[6:7], off offset:32
	v_mul_f32_e32 v6, v20, v14
	v_mul_f32_e32 v7, v20, v15
	v_cvt_pk_bf16_f32 v6, v6, v7
	v_mul_f32_e32 v7, v20, v16
	v_mul_f32_e32 v8, v20, v17
	v_cvt_pk_bf16_f32 v7, v7, v8
	global_store_dwordx2 v[18:19], v[6:7], off offset:64
	v_mul_f32_e32 v6, v20, v22
	v_mul_f32_e32 v7, v20, v23
	v_cvt_pk_bf16_f32 v6, v6, v7
	v_mul_f32_e32 v7, v20, v24
	v_mul_f32_e32 v8, v20, v25
	v_cvt_pk_bf16_f32 v7, v7, v8
	global_store_dwordx2 v[18:19], v[6:7], off offset:96
	v_mul_f32_e32 v6, v20, v26
	v_mul_f32_e32 v7, v20, v27
	v_cvt_pk_bf16_f32 v6, v6, v7
	v_mul_f32_e32 v7, v20, v28
	v_mul_f32_e32 v8, v20, v29
	v_cvt_pk_bf16_f32 v7, v7, v8
	global_store_dwordx2 v[18:19], v[6:7], off offset:128
	v_mul_f32_e32 v6, v20, v30
	v_mul_f32_e32 v7, v20, v31
	v_cvt_pk_bf16_f32 v6, v6, v7
	v_mul_f32_e32 v7, v20, v32
	v_mul_f32_e32 v8, v20, v33
	v_cvt_pk_bf16_f32 v7, v7, v8
	global_store_dwordx2 v[18:19], v[6:7], off offset:160
	v_mul_f32_e32 v6, v20, v34
	v_mul_f32_e32 v7, v20, v35
	v_cvt_pk_bf16_f32 v6, v6, v7
	v_mul_f32_e32 v7, v20, v36
	v_mul_f32_e32 v2, v20, v2
	v_mul_f32_e32 v3, v20, v3
	v_mul_f32_e32 v8, v20, v37
	v_cvt_pk_bf16_f32 v7, v7, v8
	global_store_dwordx2 v[18:19], v[6:7], off offset:192
	v_cvt_pk_bf16_f32 v2, v2, v3
	v_mul_f32_e32 v3, v20, v4
	v_mul_f32_e32 v4, v20, v5
	v_cvt_pk_bf16_f32 v3, v3, v4
	global_store_dwordx2 v[18:19], v[2:3], off offset:224
	s_cbranch_scc0 .Lre_nowait
	s_waitcnt vmcnt(0)
.Lre_nowait:
	s_barrier
	s_cbranch_scc1 .LBB9_802
